# baseline (speedup 1.0000x reference)
; #define GAS __attribute__((address_space(1)))
; #define WAIT_V(n) asm volatile("s_waitcnt vmcnt(" #n ")" ::: "memory")
; #define BAR __builtin_amdgcn_s_barrier()
; template <int K, int LD = K>
; __device__ __forceinline__ void gemm_main(const GAS bf16* A, const GAS bf16* Bt, int brow, int bcol, f32x4 (&acc)[2][2][4][2]) {
;     ...
;   const int wid = tid_ >> 6, lane = tid_ & 63, wr = wid >> 2, wc = wid & 3, fr = lane & 15, fq = lane >> 4;
; #pragma unroll
;   for (int a = 0; a < 2; ++a)
; #pragma unroll
;     for (int b = 0; b < 2; ++b)
; #pragma unroll
;       for (int m = 0; m < 4; ++m)
; #pragma unroll
;         for (int n = 0; n < 2; ++n) acc[a][b][m][n] = f32x4{0.f, 0.f, 0.f, 0.f};
;   bf16x8 At[4][2], B0[2][2], B1[2][2];
;   unsigned so0, so1;
;   { int r_, c_; stage_rc(tid_ * 16, r_, c_); so0 = (unsigned)(r_ * LD + c_) * 2u; stage_rc(tid_ * 16 + 8192, r_, c_); so1 = (unsigned)(r_ * LD + c_) * 2u; }
;   const GAS char* pA0 = (const GAS char*)A + (long)brow * LD * 2; const GAS char* pA1 = pA0 + (long)HALF * LD * 2;
;   const GAS char* pB0 = (const GAS char*)Bt + (long)bcol * LD * 2; const GAS char* pB1 = pB0 + (long)HALF * LD * 2;
;   asm volatile("" : "+s"(pA0), "+s"(pA1), "+s"(pB0), "+s"(pB1));
;   constexpr int nt = K / BK;
;   static_assert(K % 128 == 0 && K >= 256, "K");
;   if (wr == 1) BAR;
;   WAIT_V(0); BAR;
;   BAR;
.LBB0_88:
	s_or_b64 exec, exec, s[24:25]
	v_bfe_i32 v7, v136, 27, 1
	v_lshlrev_b32_e32 v5, 4, v136
	v_lshrrev_b32_e32 v7, 22, v7
	v_add_u32_e32 v7, v5, v7
	v_and_b32_e32 v7, 0xfffffc00, v7
	v_sub_u32_e32 v7, v5, v7
	v_lshrrev_b32_e32 v8, 4, v7
	v_bitop3_b32 v8, v8, v7, 32 bitop3:0x6c
	v_ashrrev_i32_e32 v7, 31, v7
	v_ashrrev_i32_e32 v6, 31, v136
	v_lshrrev_b32_e32 v7, 26, v7
	v_lshrrev_b32_e32 v6, 26, v6
	v_add_u32_e32 v7, v8, v7
	v_add_u32_e32 v6, v136, v6
	v_ashrrev_i32_e32 v7, 6, v7
	v_ashrrev_i32_e32 v6, 6, v6
	v_mul_i32_i24_e32 v10, 64, v7
	v_lshlrev_b32_e32 v9, 3, v6
	v_lshlrev_b32_e32 v6, 5, v6
	v_sub_u32_e32 v8, v8, v10
	v_and_b32_e32 v9, 0x1ffff0, v9
	v_and_b32_e32 v6, 32, v6
	v_ashrrev_i16_sdwa v8, v134, sext(v8) dst_sel:DWORD dst_unused:UNUSED_PAD src0_sel:DWORD src1_sel:BYTE_0
	v_add_u32_sdwa v6, v6, sext(v8) dst_sel:DWORD dst_unused:UNUSED_PAD src0_sel:DWORD src1_sel:WORD_0
	v_add_lshl_u32 v7, v7, v9, 11
	v_lshl_add_u32 v130, v6, 1, v7
	v_add_u32_e32 v6, 0x2000, v5
	v_ashrrev_i32_e32 v7, 31, v6
	v_lshrrev_b32_e32 v7, 22, v7
	v_add_u32_e32 v7, v6, v7
	v_ashrrev_i32_e32 v7, 10, v7
	v_mul_i32_i24_e32 v8, 0x400, v7
	v_sub_u32_e32 v6, v6, v8
	v_lshrrev_b32_e32 v8, 4, v6
	v_bitop3_b32 v6, v8, v6, 32 bitop3:0x6c
	v_ashrrev_i32_e32 v9, 31, v6
	v_lshrrev_b32_e32 v9, 26, v9
	v_add_u32_e32 v9, v6, v9
	v_lshrrev_b32_e32 v10, 6, v9
	v_and_b32_e32 v9, 0xc0, v9
	v_lshlrev_b32_e32 v8, 3, v7
	v_lshlrev_b32_e32 v7, 5, v7
	v_sub_u32_e32 v6, v6, v9
	v_and_b32_e32 v8, 0x1ffff0, v8
	v_and_b32_e32 v7, 32, v7
	v_ashrrev_i16_sdwa v6, v134, sext(v6) dst_sel:DWORD dst_unused:UNUSED_PAD src0_sel:DWORD src1_sel:BYTE_0
	v_add_u32_sdwa v6, v7, sext(v6) dst_sel:DWORD dst_unused:UNUSED_PAD src0_sel:DWORD src1_sel:WORD_0
	v_add_lshl_u32 v7, v10, v8, 11
	v_and_b32_e32 v3, 15, v136
	v_lshl_add_u32 v132, v6, 1, v7
	v_lshlrev_b32_e32 v6, 2, v136
	v_and_b32_e32 v4, 48, v136
	v_lshlrev_b32_e32 v3, 6, v3
	v_and_b32_e32 v6, 32, v6
	v_lshlrev_b32_e32 v11, 6, v136
	v_bitop3_b32 v3, v3, v6, v4 bitop3:0x36
	v_lshlrev_b32_e32 v13, 13, v2
	v_and_or_b32 v2, v11, s38, v4
	v_add_u32_e32 v7, s29, v3
	v_add_u32_e32 v8, s30, v3
	v_add_u32_e32 v9, s31, v3
	v_add_u32_e32 v10, s33, v3
	v_and_b32_e32 v12, 0x3000, v11
	v_add_u32_e32 v3, 0x100, v3
	v_xad_u32 v4, v2, v6, s34
	v_or_b32_e32 v6, 0x800, v13
	v_or_b32_e32 v11, 0x1000, v13
	v_or_b32_e32 v14, 0x1800, v13
	v_mov_b32_e32 v2, 0
	v_add_u32_e32 v145, 0x100, v5
	v_add_u32_e32 v146, s29, v5
	v_add_u32_e32 v147, s30, v5
	v_add_u32_e32 v148, s31, v5
	v_add_u32_e32 v149, s33, v5
	v_mov_b32_e32 v133, v131
	s_mov_b32 s17, -2
	v_add_u32_e32 v144, v7, v12
	v_add_u32_e32 v140, v3, v13
	v_add_u32_e32 v139, v4, v6
	v_add_u32_e32 v138, v4, v11
	v_add_u32_e32 v137, v4, v14
	v_add_u32_e32 v143, v8, v12
	v_add_u32_e32 v142, v9, v12
	v_add_u32_e32 v141, v10, v12
	v_mov_b32_e32 v3, 0
	v_mov_b64_e32 v[4:5], 0
	v_mov_b64_e32 v[6:7], 0
	v_mov_b64_e32 v[8:9], 0
	v_mov_b64_e32 v[10:11], 0
	v_mov_b64_e32 v[12:13], 0
	v_mov_b64_e32 v[14:15], 0
	v_mov_b64_e32 v[16:17], 0
	v_mov_b64_e32 v[18:19], 0
	v_mov_b64_e32 v[20:21], 0
	v_mov_b64_e32 v[22:23], 0
	v_mov_b64_e32 v[24:25], 0
	v_mov_b64_e32 v[26:27], 0
	v_mov_b64_e32 v[28:29], 0
	v_mov_b64_e32 v[30:31], 0
	v_mov_b64_e32 v[32:33], 0
	v_mov_b64_e32 v[34:35], 0
	v_mov_b64_e32 v[36:37], 0
	v_mov_b64_e32 v[38:39], 0
	v_mov_b64_e32 v[40:41], 0
	v_mov_b64_e32 v[42:43], 0
	v_mov_b64_e32 v[44:45], 0
	v_mov_b64_e32 v[46:47], 0
	v_mov_b64_e32 v[48:49], 0
	v_mov_b64_e32 v[50:51], 0
	v_mov_b64_e32 v[52:53], 0
	v_mov_b64_e32 v[54:55], 0
	v_mov_b64_e32 v[56:57], 0
	v_mov_b64_e32 v[58:59], 0
	v_mov_b64_e32 v[60:61], 0
	v_mov_b64_e32 v[62:63], 0
	v_mov_b64_e32 v[64:65], 0
	v_mov_b64_e32 v[66:67], 0
	v_mov_b64_e32 v[68:69], 0
	v_mov_b64_e32 v[70:71], 0
	v_mov_b64_e32 v[72:73], 0
	v_mov_b64_e32 v[74:75], 0
	v_mov_b64_e32 v[76:77], 0
	v_mov_b64_e32 v[78:79], 0
	v_mov_b64_e32 v[80:81], 0
	v_mov_b64_e32 v[82:83], 0
	v_mov_b64_e32 v[84:85], 0
	v_mov_b64_e32 v[86:87], 0
	v_mov_b64_e32 v[88:89], 0
	v_mov_b64_e32 v[90:91], 0
	v_mov_b64_e32 v[92:93], 0
	v_mov_b64_e32 v[94:95], 0
	v_mov_b64_e32 v[96:97], 0
	v_mov_b64_e32 v[98:99], 0
	v_mov_b64_e32 v[100:101], 0
	v_mov_b64_e32 v[102:103], 0
	v_mov_b64_e32 v[104:105], 0
	v_mov_b64_e32 v[106:107], 0
	v_mov_b64_e32 v[108:109], 0
	v_mov_b64_e32 v[110:111], 0
	v_mov_b64_e32 v[112:113], 0
	v_mov_b64_e32 v[114:115], 0
	v_mov_b64_e32 v[116:117], 0
	v_mov_b64_e32 v[118:119], 0
	v_mov_b64_e32 v[120:121], 0
	v_mov_b64_e32 v[122:123], 0
	v_mov_b64_e32 v[124:125], 0
	v_mov_b64_e32 v[126:127], 0
	v_mov_b64_e32 v[128:129], 0
	v_add_u32_e32 v151, 0xc000, v145
	v_add_u32_e32 v150, 0xe000, v145
	v_add_u32_e32 v152, 0x2000, v145
	v_add_u32_e32 v153, 0x4000, v145
	v_add_u32_e32 v154, 0x6000, v145
	v_add_u32_e32 v155, 0x8000, v145
	v_add_u32_e32 v156, 0xa000, v145
	v_add_u32_e32 v157, 0x2000, v146
	v_add_u32_e32 v158, 0x2000, v147
	v_add_u32_e32 v159, 0x2000, v148
	v_add_u32_e32 v160, 0x2000, v149
	s_waitcnt vmcnt(0)
	s_barrier
	s_barrier

; #define GAS __attribute__((address_space(1)))
; #define WAIT_V(n) asm volatile("s_waitcnt vmcnt(" #n ")" ::: "memory")
; #define BAR __builtin_amdgcn_s_barrier()
; template <int K, int LD = K>
; __device__ __forceinline__ void gemm_main(const GAS bf16* A, const GAS bf16* Bt, int brow, int bcol, f32x4 (&acc)[2][2][4][2]) {
;     ...
;   const int wid = tid_ >> 6, lane = tid_ & 63, wr = wid >> 2, wc = wid & 3, fr = lane & 15, fq = lane >> 4;
; #pragma unroll
;   for (int a = 0; a < 2; ++a)
; #pragma unroll
;     for (int b = 0; b < 2; ++b)
; #pragma unroll
;       for (int m = 0; m < 4; ++m)
; #pragma unroll
;         for (int n = 0; n < 2; ++n) acc[a][b][m][n] = f32x4{0.f, 0.f, 0.f, 0.f};
;   bf16x8 At[4][2], B0[2][2], B1[2][2];
;   unsigned so0, so1;
;   { int r_, c_; stage_rc(tid_ * 16, r_, c_); so0 = (unsigned)(r_ * LD + c_) * 2u; stage_rc(tid_ * 16 + 8192, r_, c_); so1 = (unsigned)(r_ * LD + c_) * 2u; }
;   const GAS char* pA0 = (const GAS char*)A + (long)brow * LD * 2; const GAS char* pA1 = pA0 + (long)HALF * LD * 2;
;   const GAS char* pB0 = (const GAS char*)Bt + (long)bcol * LD * 2; const GAS char* pB1 = pB0 + (long)HALF * LD * 2;
;   asm volatile("" : "+s"(pA0), "+s"(pA1), "+s"(pB0), "+s"(pB1));
;   constexpr int nt = K / BK;
;   static_assert(K % 128 == 0 && K >= 256, "K");
;   if (wr == 1) BAR;
;   WAIT_V(0); BAR;
;   BAR;
.LBB0_229:
	s_or_b64 exec, exec, s[22:23]
	v_bfe_i32 v7, v134, 27, 1
	v_lshlrev_b32_e32 v5, 4, v134
	v_lshrrev_b32_e32 v7, 22, v7
	v_add_u32_e32 v7, v5, v7
	v_and_b32_e32 v7, 0xfffffc00, v7
	v_ashrrev_i32_e32 v6, 31, v134
	v_sub_u32_e32 v7, v5, v7
	v_lshrrev_b32_e32 v6, 26, v6
	v_lshrrev_b32_e32 v8, 4, v7
	v_add_u32_e32 v6, v134, v6
	v_bitop3_b32 v8, v8, v7, 32 bitop3:0x6c
	v_ashrrev_i32_e32 v7, 31, v7
	v_ashrrev_i32_e32 v6, 6, v6
	v_lshrrev_b32_e32 v7, 26, v7
	v_lshlrev_b32_e32 v9, 3, v6
	v_add_u32_e32 v7, v8, v7
	v_and_b32_e32 v9, 0x3fffff0, v9
	v_ashrrev_i32_e32 v7, 6, v7
	v_add_u32_e32 v9, v7, v9
	v_mul_i32_i24_e32 v7, 64, v7
	v_sub_u32_e32 v7, v8, v7
	v_lshlrev_b32_e32 v6, 5, v6
	v_ashrrev_i16_sdwa v7, v154, sext(v7) dst_sel:DWORD dst_unused:UNUSED_PAD src0_sel:DWORD src1_sel:BYTE_0
	v_mul_lo_u32 v8, v9, s34
	v_bfe_i32 v7, v7, 0, 16
	v_and_or_b32 v6, v6, 32, v8
	v_add_lshl_u32 v130, v6, v7, 1
	v_add_u32_e32 v6, 0x2000, v5
	v_ashrrev_i32_e32 v7, 31, v6
	v_lshrrev_b32_e32 v7, 22, v7
	v_add_u32_e32 v7, v6, v7
	v_ashrrev_i32_e32 v7, 10, v7
	v_mul_i32_i24_e32 v8, 0x400, v7
	v_sub_u32_e32 v6, v6, v8
	v_lshrrev_b32_e32 v8, 4, v6
	v_bitop3_b32 v6, v8, v6, 32 bitop3:0x6c
	v_ashrrev_i32_e32 v9, 31, v6
	v_lshrrev_b32_e32 v9, 26, v9
	v_lshlrev_b32_e32 v8, 3, v7
	v_add_u32_e32 v9, v6, v9
	v_and_b32_e32 v8, 0x3fffff0, v8
	v_lshrrev_b32_e32 v10, 6, v9
	v_and_b32_e32 v9, 0xc0, v9
	v_add_u32_e32 v8, v10, v8
	v_sub_u32_e32 v6, v6, v9
	v_lshlrev_b32_e32 v7, 5, v7
	v_ashrrev_i16_sdwa v6, v154, sext(v6) dst_sel:DWORD dst_unused:UNUSED_PAD src0_sel:DWORD src1_sel:BYTE_0
	v_mul_lo_u32 v8, v8, s34
	v_bfe_i32 v6, v6, 0, 16
	v_and_or_b32 v7, v7, 32, v8
	v_and_b32_e32 v3, 15, v134
	v_add_lshl_u32 v132, v7, v6, 1
	v_lshlrev_b32_e32 v6, 2, v134
	v_and_b32_e32 v4, 48, v134
	v_lshlrev_b32_e32 v3, 6, v3
	v_and_b32_e32 v6, 32, v6
	v_lshlrev_b32_e32 v11, 6, v134
	v_bitop3_b32 v3, v3, v6, v4 bitop3:0x36
	v_lshlrev_b32_e32 v13, 13, v2
	v_and_or_b32 v2, v11, s40, v4
	v_add_u32_e32 v7, s36, v3
	v_add_u32_e32 v8, s37, v3
	v_add_u32_e32 v9, s38, v3
	v_add_u32_e32 v10, s39, v3
	v_and_b32_e32 v12, 0x3000, v11
	v_add_u32_e32 v3, 0x100, v3
	v_xad_u32 v4, v2, v6, s35
	v_or_b32_e32 v6, 0x800, v13
	v_or_b32_e32 v11, 0x1000, v13
	v_or_b32_e32 v14, 0x1800, v13
	v_mov_b32_e32 v2, 0
	v_add_u32_e32 v145, 0x100, v5
	v_add_u32_e32 v151, s36, v5
	v_add_u32_e32 v153, s37, v5
	v_add_u32_e32 v156, s38, v5
	v_add_u32_e32 v158, s39, v5
	v_mov_b32_e32 v133, v131
	s_mov_b32 s22, -2
	v_add_u32_e32 v144, v7, v12
	v_add_u32_e32 v138, v3, v13
	v_add_u32_e32 v137, v4, v6
	v_add_u32_e32 v136, v4, v11
	v_add_u32_e32 v135, v4, v14
	v_add_u32_e32 v143, 0xc000, v145
	v_add_u32_e32 v142, 0xe000, v145
	v_add_u32_e32 v141, v8, v12
	v_add_u32_e32 v146, 0x2000, v145
	v_add_u32_e32 v140, v9, v12
	v_add_u32_e32 v147, 0x4000, v145
	v_add_u32_e32 v148, 0x6000, v145
	v_add_u32_e32 v139, v10, v12
	v_add_u32_e32 v149, 0x8000, v145
	v_add_u32_e32 v150, 0xa000, v145
	v_add_u32_e32 v152, 0x2000, v151
	v_add_u32_e32 v155, 0x2000, v153
	v_add_u32_e32 v157, 0x2000, v156
	v_add_u32_e32 v159, 0x2000, v158
	v_mov_b32_e32 v3, 0
	v_mov_b64_e32 v[4:5], 0
	v_mov_b64_e32 v[6:7], 0
	v_mov_b64_e32 v[8:9], 0
	v_mov_b64_e32 v[10:11], 0
	v_mov_b64_e32 v[12:13], 0
	v_mov_b64_e32 v[14:15], 0
	v_mov_b64_e32 v[16:17], 0
	v_mov_b64_e32 v[18:19], 0
	v_mov_b64_e32 v[20:21], 0
	v_mov_b64_e32 v[22:23], 0
	v_mov_b64_e32 v[24:25], 0
	v_mov_b64_e32 v[26:27], 0
	v_mov_b64_e32 v[28:29], 0
	v_mov_b64_e32 v[30:31], 0
	v_mov_b64_e32 v[32:33], 0
	v_mov_b64_e32 v[34:35], 0
	v_mov_b64_e32 v[36:37], 0
	v_mov_b64_e32 v[38:39], 0
	v_mov_b64_e32 v[40:41], 0
	v_mov_b64_e32 v[42:43], 0
	v_mov_b64_e32 v[44:45], 0
	v_mov_b64_e32 v[46:47], 0
	v_mov_b64_e32 v[48:49], 0
	v_mov_b64_e32 v[50:51], 0
	v_mov_b64_e32 v[52:53], 0
	v_mov_b64_e32 v[54:55], 0
	v_mov_b64_e32 v[56:57], 0
	v_mov_b64_e32 v[58:59], 0
	v_mov_b64_e32 v[60:61], 0
	v_mov_b64_e32 v[62:63], 0
	v_mov_b64_e32 v[64:65], 0
	v_mov_b64_e32 v[66:67], 0
	v_mov_b64_e32 v[68:69], 0
	v_mov_b64_e32 v[70:71], 0
	v_mov_b64_e32 v[72:73], 0
	v_mov_b64_e32 v[74:75], 0
	v_mov_b64_e32 v[76:77], 0
	v_mov_b64_e32 v[78:79], 0
	v_mov_b64_e32 v[80:81], 0
	v_mov_b64_e32 v[82:83], 0
	v_mov_b64_e32 v[84:85], 0
	v_mov_b64_e32 v[86:87], 0
	v_mov_b64_e32 v[88:89], 0
	v_mov_b64_e32 v[90:91], 0
	v_mov_b64_e32 v[92:93], 0
	v_mov_b64_e32 v[94:95], 0
	v_mov_b64_e32 v[96:97], 0
	v_mov_b64_e32 v[98:99], 0
	v_mov_b64_e32 v[100:101], 0
	v_mov_b64_e32 v[102:103], 0
	v_mov_b64_e32 v[104:105], 0
	v_mov_b64_e32 v[106:107], 0
	v_mov_b64_e32 v[108:109], 0
	v_mov_b64_e32 v[110:111], 0
	v_mov_b64_e32 v[112:113], 0
	v_mov_b64_e32 v[114:115], 0
	v_mov_b64_e32 v[116:117], 0
	v_mov_b64_e32 v[118:119], 0
	v_mov_b64_e32 v[120:121], 0
	v_mov_b64_e32 v[122:123], 0
	v_mov_b64_e32 v[124:125], 0
	v_mov_b64_e32 v[126:127], 0
	v_mov_b64_e32 v[128:129], 0
	s_waitcnt vmcnt(0)
	s_barrier
	s_barrier

; #define GAS __attribute__((address_space(1)))
; #define WAIT_V(n) asm volatile("s_waitcnt vmcnt(" #n ")" ::: "memory")
; #define BAR __builtin_amdgcn_s_barrier()
; template <int K, int LD = K>
; __device__ __forceinline__ void gemm_main(const GAS bf16* A, const GAS bf16* Bt, int brow, int bcol, f32x4 (&acc)[2][2][4][2]) {
;     ...
;   const int wid = tid_ >> 6, lane = tid_ & 63, wr = wid >> 2, wc = wid & 3, fr = lane & 15, fq = lane >> 4;
; #pragma unroll
;   for (int a = 0; a < 2; ++a)
; #pragma unroll
;     for (int b = 0; b < 2; ++b)
; #pragma unroll
;       for (int m = 0; m < 4; ++m)
; #pragma unroll
;         for (int n = 0; n < 2; ++n) acc[a][b][m][n] = f32x4{0.f, 0.f, 0.f, 0.f};
;   bf16x8 At[4][2], B0[2][2], B1[2][2];
;   unsigned so0, so1;
;   { int r_, c_; stage_rc(tid_ * 16, r_, c_); so0 = (unsigned)(r_ * LD + c_) * 2u; stage_rc(tid_ * 16 + 8192, r_, c_); so1 = (unsigned)(r_ * LD + c_) * 2u; }
;   const GAS char* pA0 = (const GAS char*)A + (long)brow * LD * 2; const GAS char* pA1 = pA0 + (long)HALF * LD * 2;
;   const GAS char* pB0 = (const GAS char*)Bt + (long)bcol * LD * 2; const GAS char* pB1 = pB0 + (long)HALF * LD * 2;
;   asm volatile("" : "+s"(pA0), "+s"(pA1), "+s"(pB0), "+s"(pB1));
;   constexpr int nt = K / BK;
;   static_assert(K % 128 == 0 && K >= 256, "K");
;   if (wr == 1) BAR;
;   WAIT_V(0); BAR;
;   BAR;
.LBB0_345:
	s_or_b64 exec, exec, s[38:39]
	v_bfe_i32 v7, v134, 27, 1
	v_lshlrev_b32_e32 v5, 4, v134
	v_lshrrev_b32_e32 v7, 22, v7
	v_add_u32_e32 v7, v5, v7
	v_and_b32_e32 v7, 0xfffffc00, v7
	v_sub_u32_e32 v7, v5, v7
	v_lshrrev_b32_e32 v8, 4, v7
	v_bitop3_b32 v8, v8, v7, 32 bitop3:0x6c
	v_ashrrev_i32_e32 v7, 31, v7
	v_ashrrev_i32_e32 v6, 31, v134
	v_lshrrev_b32_e32 v7, 26, v7
	v_lshrrev_b32_e32 v6, 26, v6
	v_add_u32_e32 v7, v8, v7
	v_add_u32_e32 v6, v134, v6
	v_ashrrev_i32_e32 v7, 6, v7
	v_ashrrev_i32_e32 v6, 6, v6
	v_mul_i32_i24_e32 v10, 64, v7
	v_lshlrev_b32_e32 v9, 3, v6
	v_lshlrev_b32_e32 v6, 5, v6
	v_sub_u32_e32 v8, v8, v10
	v_and_b32_e32 v9, 0x1ffff0, v9
	v_and_b32_e32 v6, 32, v6
	v_ashrrev_i16_sdwa v8, v144, sext(v8) dst_sel:DWORD dst_unused:UNUSED_PAD src0_sel:DWORD src1_sel:BYTE_0
	v_add_u32_sdwa v6, v6, sext(v8) dst_sel:DWORD dst_unused:UNUSED_PAD src0_sel:DWORD src1_sel:WORD_0
	v_add_lshl_u32 v7, v7, v9, 11
	v_lshl_add_u32 v130, v6, 1, v7
	v_add_u32_e32 v6, 0x2000, v5
	v_ashrrev_i32_e32 v7, 31, v6
	v_lshrrev_b32_e32 v7, 22, v7
	v_add_u32_e32 v7, v6, v7
	v_ashrrev_i32_e32 v7, 10, v7
	v_mul_i32_i24_e32 v8, 0x400, v7
	v_sub_u32_e32 v6, v6, v8
	v_lshrrev_b32_e32 v8, 4, v6
	v_bitop3_b32 v6, v8, v6, 32 bitop3:0x6c
	v_ashrrev_i32_e32 v9, 31, v6
	v_lshrrev_b32_e32 v9, 26, v9
	v_add_u32_e32 v9, v6, v9
	v_lshrrev_b32_e32 v10, 6, v9
	v_and_b32_e32 v9, 0xc0, v9
	v_lshlrev_b32_e32 v8, 3, v7
	v_lshlrev_b32_e32 v7, 5, v7
	v_sub_u32_e32 v6, v6, v9
	v_and_b32_e32 v8, 0x1ffff0, v8
	v_and_b32_e32 v7, 32, v7
	v_ashrrev_i16_sdwa v6, v144, sext(v6) dst_sel:DWORD dst_unused:UNUSED_PAD src0_sel:DWORD src1_sel:BYTE_0
	v_add_u32_sdwa v6, v7, sext(v6) dst_sel:DWORD dst_unused:UNUSED_PAD src0_sel:DWORD src1_sel:WORD_0
	v_add_lshl_u32 v7, v10, v8, 11
	v_and_b32_e32 v3, 15, v134
	v_lshl_add_u32 v132, v6, 1, v7
	v_lshlrev_b32_e32 v6, 2, v134
	v_and_b32_e32 v4, 48, v134
	v_lshlrev_b32_e32 v3, 6, v3
	v_and_b32_e32 v6, 32, v6
	v_lshlrev_b32_e32 v11, 6, v134
	v_bitop3_b32 v3, v3, v6, v4 bitop3:0x36
	v_lshlrev_b32_e32 v13, 13, v2
	v_and_or_b32 v2, v11, s51, v4
	v_add_u32_e32 v7, s42, v3
	v_add_u32_e32 v8, s43, v3
	v_add_u32_e32 v9, s46, v3
	v_add_u32_e32 v10, s47, v3
	v_and_b32_e32 v12, 0x3000, v11
	v_add_u32_e32 v3, 0x100, v3
	v_xad_u32 v4, v2, v6, s48
	v_or_b32_e32 v6, 0x800, v13
	v_or_b32_e32 v11, 0x1000, v13
	v_or_b32_e32 v14, 0x1800, v13
	v_mov_b32_e32 v2, 0
	v_add_u32_e32 v147, 0x100, v5
	v_add_u32_e32 v153, s42, v5
	v_add_u32_e32 v155, s43, v5
	v_add_u32_e32 v157, s46, v5
	v_add_u32_e32 v159, s47, v5
	v_mov_b32_e32 v133, v131
	s_mov_b32 s5, -2
	v_add_u32_e32 v146, v7, v12
	v_add_u32_e32 v138, v3, v13
	v_add_u32_e32 v137, v4, v6
	v_add_u32_e32 v136, v4, v11
	v_add_u32_e32 v135, v4, v14
	v_add_u32_e32 v143, 0xc000, v147
	v_add_u32_e32 v142, 0xe000, v147
	v_add_u32_e32 v141, v8, v12
	v_add_u32_e32 v148, 0x2000, v147
	v_add_u32_e32 v140, v9, v12
	v_add_u32_e32 v149, 0x4000, v147
	v_add_u32_e32 v150, 0x6000, v147
	v_add_u32_e32 v139, v10, v12
	v_add_u32_e32 v151, 0x8000, v147
	v_add_u32_e32 v152, 0xa000, v147
	v_add_u32_e32 v154, 0x2000, v153
	v_add_u32_e32 v156, 0x2000, v155
	v_add_u32_e32 v158, 0x2000, v157
	v_add_u32_e32 v160, 0x2000, v159
	v_mov_b32_e32 v3, 0
	v_mov_b64_e32 v[4:5], 0
	v_mov_b64_e32 v[6:7], 0
	v_mov_b64_e32 v[8:9], 0
	v_mov_b64_e32 v[10:11], 0
	v_mov_b64_e32 v[12:13], 0
	v_mov_b64_e32 v[14:15], 0
	v_mov_b64_e32 v[16:17], 0
	v_mov_b64_e32 v[18:19], 0
	v_mov_b64_e32 v[20:21], 0
	v_mov_b64_e32 v[22:23], 0
	v_mov_b64_e32 v[24:25], 0
	v_mov_b64_e32 v[26:27], 0
	v_mov_b64_e32 v[28:29], 0
	v_mov_b64_e32 v[30:31], 0
	v_mov_b64_e32 v[32:33], 0
	v_mov_b64_e32 v[34:35], 0
	v_mov_b64_e32 v[36:37], 0
	v_mov_b64_e32 v[38:39], 0
	v_mov_b64_e32 v[40:41], 0
	v_mov_b64_e32 v[42:43], 0
	v_mov_b64_e32 v[44:45], 0
	v_mov_b64_e32 v[46:47], 0
	v_mov_b64_e32 v[48:49], 0
	v_mov_b64_e32 v[50:51], 0
	v_mov_b64_e32 v[52:53], 0
	v_mov_b64_e32 v[54:55], 0
	v_mov_b64_e32 v[56:57], 0
	v_mov_b64_e32 v[58:59], 0
	v_mov_b64_e32 v[60:61], 0
	v_mov_b64_e32 v[62:63], 0
	v_mov_b64_e32 v[64:65], 0
	v_mov_b64_e32 v[66:67], 0
	v_mov_b64_e32 v[68:69], 0
	v_mov_b64_e32 v[70:71], 0
	v_mov_b64_e32 v[72:73], 0
	v_mov_b64_e32 v[74:75], 0
	v_mov_b64_e32 v[76:77], 0
	v_mov_b64_e32 v[78:79], 0
	v_mov_b64_e32 v[80:81], 0
	v_mov_b64_e32 v[82:83], 0
	v_mov_b64_e32 v[84:85], 0
	v_mov_b64_e32 v[86:87], 0
	v_mov_b64_e32 v[88:89], 0
	v_mov_b64_e32 v[90:91], 0
	v_mov_b64_e32 v[92:93], 0
	v_mov_b64_e32 v[94:95], 0
	v_mov_b64_e32 v[96:97], 0
	v_mov_b64_e32 v[98:99], 0
	v_mov_b64_e32 v[100:101], 0
	v_mov_b64_e32 v[102:103], 0
	v_mov_b64_e32 v[104:105], 0
	v_mov_b64_e32 v[106:107], 0
	v_mov_b64_e32 v[108:109], 0
	v_mov_b64_e32 v[110:111], 0
	v_mov_b64_e32 v[112:113], 0
	v_mov_b64_e32 v[114:115], 0
	v_mov_b64_e32 v[116:117], 0
	v_mov_b64_e32 v[118:119], 0
	v_mov_b64_e32 v[120:121], 0
	v_mov_b64_e32 v[122:123], 0
	v_mov_b64_e32 v[124:125], 0
	v_mov_b64_e32 v[126:127], 0
	v_mov_b64_e32 v[128:129], 0
	s_waitcnt vmcnt(0)
	s_barrier
	s_barrier

; #define GAS __attribute__((address_space(1)))
; #define WAIT_V(n) asm volatile("s_waitcnt vmcnt(" #n ")" ::: "memory")
; #define BAR __builtin_amdgcn_s_barrier()
; template <int K, int LD = K>
; __device__ __forceinline__ void gemm_main(const GAS bf16* A, const GAS bf16* Bt, int brow, int bcol, f32x4 (&acc)[2][2][4][2]) {
;     ...
;   const int wid = tid_ >> 6, lane = tid_ & 63, wr = wid >> 2, wc = wid & 3, fr = lane & 15, fq = lane >> 4;
; #pragma unroll
;   for (int a = 0; a < 2; ++a)
; #pragma unroll
;     for (int b = 0; b < 2; ++b)
; #pragma unroll
;       for (int m = 0; m < 4; ++m)
; #pragma unroll
;         for (int n = 0; n < 2; ++n) acc[a][b][m][n] = f32x4{0.f, 0.f, 0.f, 0.f};
;   bf16x8 At[4][2], B0[2][2], B1[2][2];
;   unsigned so0, so1;
;   { int r_, c_; stage_rc(tid_ * 16, r_, c_); so0 = (unsigned)(r_ * LD + c_) * 2u; stage_rc(tid_ * 16 + 8192, r_, c_); so1 = (unsigned)(r_ * LD + c_) * 2u; }
;   const GAS char* pA0 = (const GAS char*)A + (long)brow * LD * 2; const GAS char* pA1 = pA0 + (long)HALF * LD * 2;
;   const GAS char* pB0 = (const GAS char*)Bt + (long)bcol * LD * 2; const GAS char* pB1 = pB0 + (long)HALF * LD * 2;
;   asm volatile("" : "+s"(pA0), "+s"(pA1), "+s"(pB0), "+s"(pB1));
;   constexpr int nt = K / BK;
;   static_assert(K % 128 == 0 && K >= 256, "K");
;   if (wr == 1) BAR;
;   WAIT_V(0); BAR;
;   BAR;
.LBB0_708:
	s_or_b64 exec, exec, s[30:31]
	v_bfe_i32 v6, v134, 27, 1
	v_lshlrev_b32_e32 v141, 4, v134
	v_lshrrev_b32_e32 v6, 22, v6
	v_add_u32_e32 v6, v141, v6
	v_and_b32_e32 v6, 0xfffffc00, v6
	v_sub_u32_e32 v6, v141, v6
	v_lshrrev_b32_e32 v7, 4, v6
	v_bitop3_b32 v7, v7, v6, 32 bitop3:0x6c
	v_ashrrev_i32_e32 v6, 31, v6
	v_ashrrev_i32_e32 v5, 31, v134
	v_lshrrev_b32_e32 v6, 26, v6
	v_lshrrev_b32_e32 v5, 26, v5
	v_add_u32_e32 v6, v7, v6
	v_add_u32_e32 v5, v134, v5
	v_ashrrev_i32_e32 v6, 6, v6
	v_ashrrev_i32_e32 v5, 6, v5
	v_mul_i32_i24_e32 v9, 64, v6
	v_lshlrev_b32_e32 v8, 3, v5
	v_lshlrev_b32_e32 v5, 5, v5
	v_sub_u32_e32 v7, v7, v9
	v_and_b32_e32 v8, 0x3ffff0, v8
	v_and_b32_e32 v5, 32, v5
	v_ashrrev_i16_sdwa v7, v1, sext(v7) dst_sel:DWORD dst_unused:UNUSED_PAD src0_sel:DWORD src1_sel:BYTE_0
	v_add_u32_sdwa v5, v5, sext(v7) dst_sel:DWORD dst_unused:UNUSED_PAD src0_sel:DWORD src1_sel:WORD_0
	v_add_lshl_u32 v6, v6, v8, 10
	v_lshl_add_u32 v130, v5, 1, v6
	v_add_u32_e32 v5, 0x2000, v141
	v_ashrrev_i32_e32 v6, 31, v5
	v_lshrrev_b32_e32 v6, 22, v6
	v_add_u32_e32 v6, v5, v6
	v_ashrrev_i32_e32 v6, 10, v6
	v_mul_i32_i24_e32 v7, 0x400, v6
	v_sub_u32_e32 v5, v5, v7
	v_lshrrev_b32_e32 v7, 4, v5
	v_bitop3_b32 v5, v7, v5, 32 bitop3:0x6c
	v_ashrrev_i32_e32 v8, 31, v5
	v_lshrrev_b32_e32 v8, 26, v8
	v_add_u32_e32 v8, v5, v8
	v_lshrrev_b32_e32 v9, 6, v8
	v_and_b32_e32 v8, 0xc0, v8
	v_lshlrev_b32_e32 v7, 3, v6
	v_lshlrev_b32_e32 v6, 5, v6
	v_sub_u32_e32 v5, v5, v8
	v_and_b32_e32 v7, 0x3ffff0, v7
	v_and_b32_e32 v6, 32, v6
	v_ashrrev_i16_sdwa v5, v1, sext(v5) dst_sel:DWORD dst_unused:UNUSED_PAD src0_sel:DWORD src1_sel:BYTE_0
	v_add_u32_sdwa v5, v6, sext(v5) dst_sel:DWORD dst_unused:UNUSED_PAD src0_sel:DWORD src1_sel:WORD_0
	v_add_lshl_u32 v6, v9, v7, 10
	v_and_b32_e32 v3, 15, v134
	v_lshl_add_u32 v132, v5, 1, v6
	v_lshlrev_b32_e32 v5, 2, v134
	v_and_b32_e32 v4, 48, v134
	v_lshlrev_b32_e32 v3, 6, v3
	v_and_b32_e32 v5, 32, v5
	v_lshlrev_b32_e32 v10, 6, v134
	v_bitop3_b32 v3, v3, v5, v4 bitop3:0x36
	v_lshlrev_b32_e32 v12, 13, v2
	v_and_or_b32 v2, v10, s54, v4
	v_add_u32_e32 v6, s47, v3
	v_add_u32_e32 v7, s48, v3
	v_add_u32_e32 v8, s49, v3
	v_add_u32_e32 v9, s50, v3
	v_and_b32_e32 v11, 0x3000, v10
	v_add_u32_e32 v3, 0x100, v3
	v_xad_u32 v4, v2, v5, s51
	v_or_b32_e32 v5, 0x800, v12
	v_or_b32_e32 v10, 0x1000, v12
	v_or_b32_e32 v13, 0x1800, v12
	v_mov_b32_e32 v2, 0
	v_mov_b32_e32 v133, v131
	s_mov_b32 s17, -2
	v_add_u32_e32 v143, v6, v11
	v_add_u32_e32 v138, v3, v12
	v_add_u32_e32 v137, v4, v5
	v_add_u32_e32 v136, v4, v10
	v_add_u32_e32 v135, v4, v13
	v_add_u32_e32 v142, v7, v11
	v_add_u32_e32 v140, v8, v11
	v_add_u32_e32 v139, v9, v11
	v_mov_b32_e32 v3, 0
	v_mov_b64_e32 v[4:5], 0
	v_mov_b64_e32 v[6:7], 0
	v_mov_b64_e32 v[8:9], 0
	v_mov_b64_e32 v[10:11], 0
	v_mov_b64_e32 v[12:13], 0
	v_mov_b64_e32 v[14:15], 0
	v_mov_b64_e32 v[16:17], 0
	v_mov_b64_e32 v[18:19], 0
	v_mov_b64_e32 v[20:21], 0
	v_mov_b64_e32 v[22:23], 0
	v_mov_b64_e32 v[24:25], 0
	v_mov_b64_e32 v[26:27], 0
	v_mov_b64_e32 v[28:29], 0
	v_mov_b64_e32 v[30:31], 0
	v_mov_b64_e32 v[32:33], 0
	v_mov_b64_e32 v[34:35], 0
	v_mov_b64_e32 v[36:37], 0
	v_mov_b64_e32 v[38:39], 0
	v_mov_b64_e32 v[40:41], 0
	v_mov_b64_e32 v[42:43], 0
	v_mov_b64_e32 v[44:45], 0
	v_mov_b64_e32 v[46:47], 0
	v_mov_b64_e32 v[48:49], 0
	v_mov_b64_e32 v[50:51], 0
	v_mov_b64_e32 v[52:53], 0
	v_mov_b64_e32 v[54:55], 0
	v_mov_b64_e32 v[56:57], 0
	v_mov_b64_e32 v[58:59], 0
	v_mov_b64_e32 v[60:61], 0
	v_mov_b64_e32 v[62:63], 0
	v_mov_b64_e32 v[64:65], 0
	v_mov_b64_e32 v[66:67], 0
	v_mov_b64_e32 v[68:69], 0
	v_mov_b64_e32 v[70:71], 0
	v_mov_b64_e32 v[72:73], 0
	v_mov_b64_e32 v[74:75], 0
	v_mov_b64_e32 v[76:77], 0
	v_mov_b64_e32 v[78:79], 0
	v_mov_b64_e32 v[80:81], 0
	v_mov_b64_e32 v[82:83], 0
	v_mov_b64_e32 v[84:85], 0
	v_mov_b64_e32 v[86:87], 0
	v_mov_b64_e32 v[88:89], 0
	v_mov_b64_e32 v[90:91], 0
	v_mov_b64_e32 v[92:93], 0
	v_mov_b64_e32 v[94:95], 0
	v_mov_b64_e32 v[96:97], 0
	v_mov_b64_e32 v[98:99], 0
	v_mov_b64_e32 v[100:101], 0
	v_mov_b64_e32 v[102:103], 0
	v_mov_b64_e32 v[104:105], 0
	v_mov_b64_e32 v[106:107], 0
	v_mov_b64_e32 v[108:109], 0
	v_mov_b64_e32 v[110:111], 0
	v_mov_b64_e32 v[112:113], 0
	v_mov_b64_e32 v[114:115], 0
	v_mov_b64_e32 v[116:117], 0
	v_mov_b64_e32 v[118:119], 0
	v_mov_b64_e32 v[120:121], 0
	v_mov_b64_e32 v[122:123], 0
	v_mov_b64_e32 v[124:125], 0
	v_mov_b64_e32 v[126:127], 0
	v_mov_b64_e32 v[128:129], 0
	s_waitcnt vmcnt(0)
	s_barrier
	s_barrier

; #define GAS __attribute__((address_space(1)))
; #define WAIT_V(n) asm volatile("s_waitcnt vmcnt(" #n ")" ::: "memory")
; #define BAR __builtin_amdgcn_s_barrier()
; template <int K, int LD = K>
; __device__ __forceinline__ void gemm_main(const GAS bf16* A, const GAS bf16* Bt, int brow, int bcol, f32x4 (&acc)[2][2][4][2]) {
;     ...
;   const int wid = tid_ >> 6, lane = tid_ & 63, wr = wid >> 2, wc = wid & 3, fr = lane & 15, fq = lane >> 4;
; #pragma unroll
;   for (int a = 0; a < 2; ++a)
; #pragma unroll
;     for (int b = 0; b < 2; ++b)
; #pragma unroll
;       for (int m = 0; m < 4; ++m)
; #pragma unroll
;         for (int n = 0; n < 2; ++n) acc[a][b][m][n] = f32x4{0.f, 0.f, 0.f, 0.f};
;   bf16x8 At[4][2], B0[2][2], B1[2][2];
;   unsigned so0, so1;
;   { int r_, c_; stage_rc(tid_ * 16, r_, c_); so0 = (unsigned)(r_ * LD + c_) * 2u; stage_rc(tid_ * 16 + 8192, r_, c_); so1 = (unsigned)(r_ * LD + c_) * 2u; }
;   const GAS char* pA0 = (const GAS char*)A + (long)brow * LD * 2; const GAS char* pA1 = pA0 + (long)HALF * LD * 2;
;   const GAS char* pB0 = (const GAS char*)Bt + (long)bcol * LD * 2; const GAS char* pB1 = pB0 + (long)HALF * LD * 2;
;   asm volatile("" : "+s"(pA0), "+s"(pA1), "+s"(pB0), "+s"(pB1));
;   constexpr int nt = K / BK;
;   static_assert(K % 128 == 0 && K >= 256, "K");
;   if (wr == 1) BAR;
;   WAIT_V(0); BAR;
;   BAR;
.LBB0_714:
	s_or_b64 exec, exec, s[28:29]
	v_bfe_i32 v6, v134, 27, 1
	v_lshlrev_b32_e32 v141, 4, v134
	v_lshrrev_b32_e32 v6, 22, v6
	v_add_u32_e32 v6, v141, v6
	v_and_b32_e32 v6, 0xfffffc00, v6
	v_sub_u32_e32 v6, v141, v6
	v_lshrrev_b32_e32 v7, 4, v6
	v_bitop3_b32 v7, v7, v6, 32 bitop3:0x6c
	v_ashrrev_i32_e32 v6, 31, v6
	v_ashrrev_i32_e32 v5, 31, v134
	v_lshrrev_b32_e32 v6, 26, v6
	v_lshrrev_b32_e32 v5, 26, v5
	v_add_u32_e32 v6, v7, v6
	v_add_u32_e32 v5, v134, v5
	v_ashrrev_i32_e32 v6, 6, v6
	v_ashrrev_i32_e32 v5, 6, v5
	v_mul_i32_i24_e32 v9, 64, v6
	v_lshlrev_b32_e32 v8, 3, v5
	v_lshlrev_b32_e32 v5, 5, v5
	v_sub_u32_e32 v7, v7, v9
	v_and_b32_e32 v8, 0x3ffff0, v8
	v_and_b32_e32 v5, 32, v5
	v_ashrrev_i16_sdwa v7, v1, sext(v7) dst_sel:DWORD dst_unused:UNUSED_PAD src0_sel:DWORD src1_sel:BYTE_0
	v_add_u32_sdwa v5, v5, sext(v7) dst_sel:DWORD dst_unused:UNUSED_PAD src0_sel:DWORD src1_sel:WORD_0
	v_add_lshl_u32 v6, v6, v8, 10
	v_lshl_add_u32 v130, v5, 1, v6
	v_add_u32_e32 v5, 0x2000, v141
	v_ashrrev_i32_e32 v6, 31, v5
	v_lshrrev_b32_e32 v6, 22, v6
	v_add_u32_e32 v6, v5, v6
	v_ashrrev_i32_e32 v6, 10, v6
	v_mul_i32_i24_e32 v7, 0x400, v6
	v_sub_u32_e32 v5, v5, v7
	v_lshrrev_b32_e32 v7, 4, v5
	v_bitop3_b32 v5, v7, v5, 32 bitop3:0x6c
	v_ashrrev_i32_e32 v8, 31, v5
	v_lshrrev_b32_e32 v8, 26, v8
	v_add_u32_e32 v8, v5, v8
	v_lshrrev_b32_e32 v9, 6, v8
	v_and_b32_e32 v8, 0xc0, v8
	v_lshlrev_b32_e32 v7, 3, v6
	v_lshlrev_b32_e32 v6, 5, v6
	v_sub_u32_e32 v5, v5, v8
	v_and_b32_e32 v7, 0x3ffff0, v7
	v_and_b32_e32 v6, 32, v6
	v_ashrrev_i16_sdwa v5, v1, sext(v5) dst_sel:DWORD dst_unused:UNUSED_PAD src0_sel:DWORD src1_sel:BYTE_0
	v_add_u32_sdwa v5, v6, sext(v5) dst_sel:DWORD dst_unused:UNUSED_PAD src0_sel:DWORD src1_sel:WORD_0
	v_add_lshl_u32 v6, v9, v7, 10
	v_and_b32_e32 v3, 15, v134
	v_lshl_add_u32 v132, v5, 1, v6
	v_lshlrev_b32_e32 v5, 2, v134
	v_and_b32_e32 v4, 48, v134
	v_lshlrev_b32_e32 v3, 6, v3
	v_and_b32_e32 v5, 32, v5
	v_lshlrev_b32_e32 v10, 6, v134
	v_bitop3_b32 v3, v3, v5, v4 bitop3:0x36
	v_lshlrev_b32_e32 v12, 13, v2
	v_and_or_b32 v2, v10, s54, v4
	v_add_u32_e32 v6, s47, v3
	v_add_u32_e32 v7, s48, v3
	v_add_u32_e32 v8, s49, v3
	v_add_u32_e32 v9, s50, v3
	v_and_b32_e32 v11, 0x3000, v10
	v_add_u32_e32 v3, 0x100, v3
	v_xad_u32 v4, v2, v5, s51
	v_or_b32_e32 v5, 0x800, v12
	v_or_b32_e32 v10, 0x1000, v12
	v_or_b32_e32 v13, 0x1800, v12
	v_mov_b32_e32 v2, 0
	v_mov_b32_e32 v133, v131
	s_mov_b32 s17, -2
	v_add_u32_e32 v143, v6, v11
	v_add_u32_e32 v138, v3, v12
	v_add_u32_e32 v137, v4, v5
	v_add_u32_e32 v136, v4, v10
	v_add_u32_e32 v135, v4, v13
	v_add_u32_e32 v142, v7, v11
	v_add_u32_e32 v140, v8, v11
	v_add_u32_e32 v139, v9, v11
	v_mov_b32_e32 v3, 0
	v_mov_b64_e32 v[4:5], 0
	v_mov_b64_e32 v[6:7], 0
	v_mov_b64_e32 v[8:9], 0
	v_mov_b64_e32 v[10:11], 0
	v_mov_b64_e32 v[12:13], 0
	v_mov_b64_e32 v[14:15], 0
	v_mov_b64_e32 v[16:17], 0
	v_mov_b64_e32 v[18:19], 0
	v_mov_b64_e32 v[20:21], 0
	v_mov_b64_e32 v[22:23], 0
	v_mov_b64_e32 v[24:25], 0
	v_mov_b64_e32 v[26:27], 0
	v_mov_b64_e32 v[28:29], 0
	v_mov_b64_e32 v[30:31], 0
	v_mov_b64_e32 v[32:33], 0
	v_mov_b64_e32 v[34:35], 0
	v_mov_b64_e32 v[36:37], 0
	v_mov_b64_e32 v[38:39], 0
	v_mov_b64_e32 v[40:41], 0
	v_mov_b64_e32 v[42:43], 0
	v_mov_b64_e32 v[44:45], 0
	v_mov_b64_e32 v[46:47], 0
	v_mov_b64_e32 v[48:49], 0
	v_mov_b64_e32 v[50:51], 0
	v_mov_b64_e32 v[52:53], 0
	v_mov_b64_e32 v[54:55], 0
	v_mov_b64_e32 v[56:57], 0
	v_mov_b64_e32 v[58:59], 0
	v_mov_b64_e32 v[60:61], 0
	v_mov_b64_e32 v[62:63], 0
	v_mov_b64_e32 v[64:65], 0
	v_mov_b64_e32 v[66:67], 0
	v_mov_b64_e32 v[68:69], 0
	v_mov_b64_e32 v[70:71], 0
	v_mov_b64_e32 v[72:73], 0
	v_mov_b64_e32 v[74:75], 0
	v_mov_b64_e32 v[76:77], 0
	v_mov_b64_e32 v[78:79], 0
	v_mov_b64_e32 v[80:81], 0
	v_mov_b64_e32 v[82:83], 0
	v_mov_b64_e32 v[84:85], 0
	v_mov_b64_e32 v[86:87], 0
	v_mov_b64_e32 v[88:89], 0
	v_mov_b64_e32 v[90:91], 0
	v_mov_b64_e32 v[92:93], 0
	v_mov_b64_e32 v[94:95], 0
	v_mov_b64_e32 v[96:97], 0
	v_mov_b64_e32 v[98:99], 0
	v_mov_b64_e32 v[100:101], 0
	v_mov_b64_e32 v[102:103], 0
	v_mov_b64_e32 v[104:105], 0
	v_mov_b64_e32 v[106:107], 0
	v_mov_b64_e32 v[108:109], 0
	v_mov_b64_e32 v[110:111], 0
	v_mov_b64_e32 v[112:113], 0
	v_mov_b64_e32 v[114:115], 0
	v_mov_b64_e32 v[116:117], 0
	v_mov_b64_e32 v[118:119], 0
	v_mov_b64_e32 v[120:121], 0
	v_mov_b64_e32 v[122:123], 0
	v_mov_b64_e32 v[124:125], 0
	v_mov_b64_e32 v[126:127], 0
	v_mov_b64_e32 v[128:129], 0
	s_waitcnt vmcnt(0)
	s_barrier
	s_barrier

; #define GAS __attribute__((address_space(1)))
; #define WAIT_V(n) asm volatile("s_waitcnt vmcnt(" #n ")" ::: "memory")
; #define BAR __builtin_amdgcn_s_barrier()
; template <int K, int LD = K>
; __device__ __forceinline__ void gemm_main(const GAS bf16* A, const GAS bf16* Bt, int brow, int bcol, f32x4 (&acc)[2][2][4][2]) {
;     ...
;   const int wid = tid_ >> 6, lane = tid_ & 63, wr = wid >> 2, wc = wid & 3, fr = lane & 15, fq = lane >> 4;
; #pragma unroll
;   for (int a = 0; a < 2; ++a)
; #pragma unroll
;     for (int b = 0; b < 2; ++b)
; #pragma unroll
;       for (int m = 0; m < 4; ++m)
; #pragma unroll
;         for (int n = 0; n < 2; ++n) acc[a][b][m][n] = f32x4{0.f, 0.f, 0.f, 0.f};
;   bf16x8 At[4][2], B0[2][2], B1[2][2];
;   unsigned so0, so1;
;   { int r_, c_; stage_rc(tid_ * 16, r_, c_); so0 = (unsigned)(r_ * LD + c_) * 2u; stage_rc(tid_ * 16 + 8192, r_, c_); so1 = (unsigned)(r_ * LD + c_) * 2u; }
;   const GAS char* pA0 = (const GAS char*)A + (long)brow * LD * 2; const GAS char* pA1 = pA0 + (long)HALF * LD * 2;
;   const GAS char* pB0 = (const GAS char*)Bt + (long)bcol * LD * 2; const GAS char* pB1 = pB0 + (long)HALF * LD * 2;
;   asm volatile("" : "+s"(pA0), "+s"(pA1), "+s"(pB0), "+s"(pB1));
;   constexpr int nt = K / BK;
;   static_assert(K % 128 == 0 && K >= 256, "K");
;   if (wr == 1) BAR;
;   WAIT_V(0); BAR;
;   BAR;
.LBB0_766:
	s_or_b64 exec, exec, s[22:23]
	v_bfe_i32 v7, v134, 27, 1
	v_lshlrev_b32_e32 v5, 4, v134
	v_lshrrev_b32_e32 v7, 22, v7
	v_add_u32_e32 v7, v5, v7
	v_and_b32_e32 v7, 0xfffffc00, v7
	v_sub_u32_e32 v7, v5, v7
	v_lshrrev_b32_e32 v8, 4, v7
	v_bitop3_b32 v8, v8, v7, 32 bitop3:0x6c
	v_ashrrev_i32_e32 v7, 31, v7
	v_ashrrev_i32_e32 v6, 31, v134
	v_lshrrev_b32_e32 v7, 26, v7
	v_lshrrev_b32_e32 v6, 26, v6
	v_add_u32_e32 v7, v8, v7
	v_add_u32_e32 v6, v134, v6
	v_ashrrev_i32_e32 v7, 6, v7
	v_ashrrev_i32_e32 v6, 6, v6
	v_mul_i32_i24_e32 v10, 64, v7
	v_lshlrev_b32_e32 v9, 3, v6
	v_lshlrev_b32_e32 v6, 5, v6
	v_sub_u32_e32 v8, v8, v10
	v_and_b32_e32 v9, 0x1ffff0, v9
	v_and_b32_e32 v6, 32, v6
	v_ashrrev_i16_sdwa v8, v1, sext(v8) dst_sel:DWORD dst_unused:UNUSED_PAD src0_sel:DWORD src1_sel:BYTE_0
	v_add_u32_sdwa v6, v6, sext(v8) dst_sel:DWORD dst_unused:UNUSED_PAD src0_sel:DWORD src1_sel:WORD_0
	v_add_lshl_u32 v7, v7, v9, 11
	v_lshl_add_u32 v130, v6, 1, v7
	v_add_u32_e32 v6, 0x2000, v5
	v_ashrrev_i32_e32 v7, 31, v6
	v_lshrrev_b32_e32 v7, 22, v7
	v_add_u32_e32 v7, v6, v7
	v_ashrrev_i32_e32 v7, 10, v7
	v_mul_i32_i24_e32 v8, 0x400, v7
	v_sub_u32_e32 v6, v6, v8
	v_lshrrev_b32_e32 v8, 4, v6
	v_bitop3_b32 v6, v8, v6, 32 bitop3:0x6c
	v_ashrrev_i32_e32 v9, 31, v6
	v_lshrrev_b32_e32 v9, 26, v9
	v_add_u32_e32 v9, v6, v9
	v_lshrrev_b32_e32 v10, 6, v9
	v_and_b32_e32 v9, 0xc0, v9
	v_lshlrev_b32_e32 v8, 3, v7
	v_lshlrev_b32_e32 v7, 5, v7
	v_sub_u32_e32 v6, v6, v9
	v_and_b32_e32 v8, 0x1ffff0, v8
	v_and_b32_e32 v7, 32, v7
	v_ashrrev_i16_sdwa v6, v1, sext(v6) dst_sel:DWORD dst_unused:UNUSED_PAD src0_sel:DWORD src1_sel:BYTE_0
	v_add_u32_sdwa v6, v7, sext(v6) dst_sel:DWORD dst_unused:UNUSED_PAD src0_sel:DWORD src1_sel:WORD_0
	v_add_lshl_u32 v7, v10, v8, 11
	v_and_b32_e32 v3, 15, v134
	v_lshl_add_u32 v132, v6, 1, v7
	v_lshlrev_b32_e32 v6, 2, v134
	v_and_b32_e32 v4, 48, v134
	v_lshlrev_b32_e32 v3, 6, v3
	v_and_b32_e32 v6, 32, v6
	v_lshlrev_b32_e32 v11, 6, v134
	v_bitop3_b32 v3, v3, v6, v4 bitop3:0x36
	v_lshlrev_b32_e32 v13, 13, v2
	v_and_or_b32 v2, v11, s39, v4
	v_add_u32_e32 v7, s35, v3
	v_add_u32_e32 v8, s36, v3
	v_add_u32_e32 v9, s37, v3
	v_add_u32_e32 v10, s38, v3
	v_and_b32_e32 v12, 0x3000, v11
	v_add_u32_e32 v3, 0x100, v3
	v_xad_u32 v4, v2, v6, s34
	v_or_b32_e32 v6, 0x800, v13
	v_or_b32_e32 v11, 0x1000, v13
	v_or_b32_e32 v14, 0x1800, v13
	v_mov_b32_e32 v2, 0
	v_add_u32_e32 v145, 0x100, v5
	v_add_u32_e32 v151, s35, v5
	v_add_u32_e32 v153, s36, v5
	v_add_u32_e32 v155, s37, v5
	v_add_u32_e32 v157, s38, v5
	v_mov_b32_e32 v133, v131
	s_mov_b32 s15, -2
	v_add_u32_e32 v144, v7, v12
	v_add_u32_e32 v138, v3, v13
	v_add_u32_e32 v137, v4, v6
	v_add_u32_e32 v136, v4, v11
	v_add_u32_e32 v135, v4, v14
	v_add_u32_e32 v143, 0xc000, v145
	v_add_u32_e32 v142, 0xe000, v145
	v_add_u32_e32 v141, v8, v12
	v_add_u32_e32 v146, 0x2000, v145
	v_add_u32_e32 v140, v9, v12
	v_add_u32_e32 v147, 0x4000, v145
	v_add_u32_e32 v148, 0x6000, v145
	v_add_u32_e32 v139, v10, v12
	v_add_u32_e32 v149, 0x8000, v145
	v_add_u32_e32 v150, 0xa000, v145
	v_add_u32_e32 v152, 0x2000, v151
	v_add_u32_e32 v154, 0x2000, v153
	v_add_u32_e32 v156, 0x2000, v155
	v_add_u32_e32 v158, 0x2000, v157
	v_mov_b32_e32 v3, 0
	v_mov_b64_e32 v[4:5], 0
	v_mov_b64_e32 v[6:7], 0
	v_mov_b64_e32 v[8:9], 0
	v_mov_b64_e32 v[10:11], 0
	v_mov_b64_e32 v[12:13], 0
	v_mov_b64_e32 v[14:15], 0
	v_mov_b64_e32 v[16:17], 0
	v_mov_b64_e32 v[18:19], 0
	v_mov_b64_e32 v[20:21], 0
	v_mov_b64_e32 v[22:23], 0
	v_mov_b64_e32 v[24:25], 0
	v_mov_b64_e32 v[26:27], 0
	v_mov_b64_e32 v[28:29], 0
	v_mov_b64_e32 v[30:31], 0
	v_mov_b64_e32 v[32:33], 0
	v_mov_b64_e32 v[34:35], 0
	v_mov_b64_e32 v[36:37], 0
	v_mov_b64_e32 v[38:39], 0
	v_mov_b64_e32 v[40:41], 0
	v_mov_b64_e32 v[42:43], 0
	v_mov_b64_e32 v[44:45], 0
	v_mov_b64_e32 v[46:47], 0
	v_mov_b64_e32 v[48:49], 0
	v_mov_b64_e32 v[50:51], 0
	v_mov_b64_e32 v[52:53], 0
	v_mov_b64_e32 v[54:55], 0
	v_mov_b64_e32 v[56:57], 0
	v_mov_b64_e32 v[58:59], 0
	v_mov_b64_e32 v[60:61], 0
	v_mov_b64_e32 v[62:63], 0
	v_mov_b64_e32 v[64:65], 0
	v_mov_b64_e32 v[66:67], 0
	v_mov_b64_e32 v[68:69], 0
	v_mov_b64_e32 v[70:71], 0
	v_mov_b64_e32 v[72:73], 0
	v_mov_b64_e32 v[74:75], 0
	v_mov_b64_e32 v[76:77], 0
	v_mov_b64_e32 v[78:79], 0
	v_mov_b64_e32 v[80:81], 0
	v_mov_b64_e32 v[82:83], 0
	v_mov_b64_e32 v[84:85], 0
	v_mov_b64_e32 v[86:87], 0
	v_mov_b64_e32 v[88:89], 0
	v_mov_b64_e32 v[90:91], 0
	v_mov_b64_e32 v[92:93], 0
	v_mov_b64_e32 v[94:95], 0
	v_mov_b64_e32 v[96:97], 0
	v_mov_b64_e32 v[98:99], 0
	v_mov_b64_e32 v[100:101], 0
	v_mov_b64_e32 v[102:103], 0
	v_mov_b64_e32 v[104:105], 0
	v_mov_b64_e32 v[106:107], 0
	v_mov_b64_e32 v[108:109], 0
	v_mov_b64_e32 v[110:111], 0
	v_mov_b64_e32 v[112:113], 0
	v_mov_b64_e32 v[114:115], 0
	v_mov_b64_e32 v[116:117], 0
	v_mov_b64_e32 v[118:119], 0
	v_mov_b64_e32 v[120:121], 0
	v_mov_b64_e32 v[122:123], 0
	v_mov_b64_e32 v[124:125], 0
	v_mov_b64_e32 v[126:127], 0
	v_mov_b64_e32 v[128:129], 0
	s_waitcnt vmcnt(0)
	s_barrier
	s_barrier

; #define GAS __attribute__((address_space(1)))
; #define WAIT_V(n) asm volatile("s_waitcnt vmcnt(" #n ")" ::: "memory")
; #define BAR __builtin_amdgcn_s_barrier()
; template <int K, int LD = K>
; __device__ __forceinline__ void gemm_main(const GAS bf16* A, const GAS bf16* Bt, int brow, int bcol, f32x4 (&acc)[2][2][4][2]) {
;     ...
;   const int wid = tid_ >> 6, lane = tid_ & 63, wr = wid >> 2, wc = wid & 3, fr = lane & 15, fq = lane >> 4;
; #pragma unroll
;   for (int a = 0; a < 2; ++a)
; #pragma unroll
;     for (int b = 0; b < 2; ++b)
; #pragma unroll
;       for (int m = 0; m < 4; ++m)
; #pragma unroll
;         for (int n = 0; n < 2; ++n) acc[a][b][m][n] = f32x4{0.f, 0.f, 0.f, 0.f};
;   bf16x8 At[4][2], B0[2][2], B1[2][2];
;   unsigned so0, so1;
;   { int r_, c_; stage_rc(tid_ * 16, r_, c_); so0 = (unsigned)(r_ * LD + c_) * 2u; stage_rc(tid_ * 16 + 8192, r_, c_); so1 = (unsigned)(r_ * LD + c_) * 2u; }
;   const GAS char* pA0 = (const GAS char*)A + (long)brow * LD * 2; const GAS char* pA1 = pA0 + (long)HALF * LD * 2;
;   const GAS char* pB0 = (const GAS char*)Bt + (long)bcol * LD * 2; const GAS char* pB1 = pB0 + (long)HALF * LD * 2;
;   asm volatile("" : "+s"(pA0), "+s"(pA1), "+s"(pB0), "+s"(pB1));
;   constexpr int nt = K / BK;
;   static_assert(K % 128 == 0 && K >= 256, "K");
;   if (wr == 1) BAR;
;   WAIT_V(0); BAR;
;   BAR;
.LBB0_883:
	s_or_b64 exec, exec, s[22:23]
	v_bfe_i32 v7, v135, 27, 1
	v_lshlrev_b32_e32 v5, 4, v135
	v_lshrrev_b32_e32 v7, 22, v7
	v_add_u32_e32 v7, v5, v7
	v_and_b32_e32 v7, 0xfffffc00, v7
	v_sub_u32_e32 v7, v5, v7
	v_lshrrev_b32_e32 v8, 4, v7
	v_bitop3_b32 v8, v8, v7, 32 bitop3:0x6c
	v_ashrrev_i32_e32 v7, 31, v7
	v_ashrrev_i32_e32 v6, 31, v135
	v_lshrrev_b32_e32 v7, 26, v7
	v_lshrrev_b32_e32 v6, 26, v6
	v_add_u32_e32 v7, v8, v7
	v_add_u32_e32 v6, v135, v6
	v_ashrrev_i32_e32 v7, 6, v7
	v_ashrrev_i32_e32 v6, 6, v6
	v_mul_i32_i24_e32 v10, 64, v7
	v_lshlrev_b32_e32 v9, 3, v6
	v_lshlrev_b32_e32 v6, 5, v6
	v_sub_u32_e32 v8, v8, v10
	v_and_b32_e32 v9, 0x1ffff0, v9
	v_and_b32_e32 v6, 32, v6
	v_ashrrev_i16_sdwa v8, v1, sext(v8) dst_sel:DWORD dst_unused:UNUSED_PAD src0_sel:DWORD src1_sel:BYTE_0
	v_add_u32_sdwa v6, v6, sext(v8) dst_sel:DWORD dst_unused:UNUSED_PAD src0_sel:DWORD src1_sel:WORD_0
	v_add_lshl_u32 v7, v7, v9, 11
	v_lshl_add_u32 v130, v6, 1, v7
	v_add_u32_e32 v6, 0x2000, v5
	v_ashrrev_i32_e32 v7, 31, v6
	v_lshrrev_b32_e32 v7, 22, v7
	v_add_u32_e32 v7, v6, v7
	v_ashrrev_i32_e32 v7, 10, v7
	v_mul_i32_i24_e32 v8, 0x400, v7
	v_sub_u32_e32 v6, v6, v8
	v_lshrrev_b32_e32 v8, 4, v6
	v_bitop3_b32 v6, v8, v6, 32 bitop3:0x6c
	v_ashrrev_i32_e32 v9, 31, v6
	v_lshrrev_b32_e32 v9, 26, v9
	v_add_u32_e32 v9, v6, v9
	v_lshrrev_b32_e32 v10, 6, v9
	v_and_b32_e32 v9, 0xc0, v9
	v_lshlrev_b32_e32 v8, 3, v7
	v_lshlrev_b32_e32 v7, 5, v7
	v_sub_u32_e32 v6, v6, v9
	v_and_b32_e32 v8, 0x1ffff0, v8
	v_and_b32_e32 v7, 32, v7
	v_ashrrev_i16_sdwa v6, v1, sext(v6) dst_sel:DWORD dst_unused:UNUSED_PAD src0_sel:DWORD src1_sel:BYTE_0
	v_add_u32_sdwa v6, v7, sext(v6) dst_sel:DWORD dst_unused:UNUSED_PAD src0_sel:DWORD src1_sel:WORD_0
	v_add_lshl_u32 v7, v10, v8, 11
	v_and_b32_e32 v3, 15, v135
	v_lshl_add_u32 v132, v6, 1, v7
	v_lshlrev_b32_e32 v6, 2, v135
	v_and_b32_e32 v4, 48, v135
	v_lshlrev_b32_e32 v3, 6, v3
	v_and_b32_e32 v6, 32, v6
	v_lshlrev_b32_e32 v11, 6, v135
	v_bitop3_b32 v3, v3, v6, v4 bitop3:0x36
	v_lshlrev_b32_e32 v13, 13, v2
	v_and_or_b32 v2, v11, s38, v4
	v_add_u32_e32 v7, s29, v3
	v_add_u32_e32 v8, s30, v3
	v_add_u32_e32 v9, s31, v3
	v_add_u32_e32 v10, s33, v3
	v_and_b32_e32 v12, 0x3000, v11
	v_add_u32_e32 v3, 0x100, v3
	v_xad_u32 v4, v2, v6, s34
	v_or_b32_e32 v6, 0x800, v13
	v_or_b32_e32 v11, 0x1000, v13
	v_or_b32_e32 v14, 0x1800, v13
	v_mov_b32_e32 v2, 0
	v_add_u32_e32 v146, 0x100, v5
	v_add_u32_e32 v152, s29, v5
	v_add_u32_e32 v154, s30, v5
	v_add_u32_e32 v156, s31, v5
	v_add_u32_e32 v158, s33, v5
	v_mov_b32_e32 v133, v131
	s_mov_b32 s15, -2
	v_add_u32_e32 v145, v7, v12
	v_add_u32_e32 v139, v3, v13
	v_add_u32_e32 v138, v4, v6
	v_add_u32_e32 v137, v4, v11
	v_add_u32_e32 v136, v4, v14
	v_add_u32_e32 v144, 0xc000, v146
	v_add_u32_e32 v143, 0xe000, v146
	v_add_u32_e32 v142, v8, v12
	v_add_u32_e32 v147, 0x2000, v146
	v_add_u32_e32 v141, v9, v12
	v_add_u32_e32 v148, 0x4000, v146
	v_add_u32_e32 v149, 0x6000, v146
	v_add_u32_e32 v140, v10, v12
	v_add_u32_e32 v150, 0x8000, v146
	v_add_u32_e32 v151, 0xa000, v146
	v_add_u32_e32 v153, 0x2000, v152
	v_add_u32_e32 v155, 0x2000, v154
	v_add_u32_e32 v157, 0x2000, v156
	v_add_u32_e32 v159, 0x2000, v158
	v_mov_b32_e32 v3, 0
	v_mov_b64_e32 v[4:5], 0
	v_mov_b64_e32 v[6:7], 0
	v_mov_b64_e32 v[8:9], 0
	v_mov_b64_e32 v[10:11], 0
	v_mov_b64_e32 v[12:13], 0
	v_mov_b64_e32 v[14:15], 0
	v_mov_b64_e32 v[16:17], 0
	v_mov_b64_e32 v[18:19], 0
	v_mov_b64_e32 v[20:21], 0
	v_mov_b64_e32 v[22:23], 0
	v_mov_b64_e32 v[24:25], 0
	v_mov_b64_e32 v[26:27], 0
	v_mov_b64_e32 v[28:29], 0
	v_mov_b64_e32 v[30:31], 0
	v_mov_b64_e32 v[32:33], 0
	v_mov_b64_e32 v[34:35], 0
	v_mov_b64_e32 v[36:37], 0
	v_mov_b64_e32 v[38:39], 0
	v_mov_b64_e32 v[40:41], 0
	v_mov_b64_e32 v[42:43], 0
	v_mov_b64_e32 v[44:45], 0
	v_mov_b64_e32 v[46:47], 0
	v_mov_b64_e32 v[48:49], 0
	v_mov_b64_e32 v[50:51], 0
	v_mov_b64_e32 v[52:53], 0
	v_mov_b64_e32 v[54:55], 0
	v_mov_b64_e32 v[56:57], 0
	v_mov_b64_e32 v[58:59], 0
	v_mov_b64_e32 v[60:61], 0
	v_mov_b64_e32 v[62:63], 0
	v_mov_b64_e32 v[64:65], 0
	v_mov_b64_e32 v[66:67], 0
	v_mov_b64_e32 v[68:69], 0
	v_mov_b64_e32 v[70:71], 0
	v_mov_b64_e32 v[72:73], 0
	v_mov_b64_e32 v[74:75], 0
	v_mov_b64_e32 v[76:77], 0
	v_mov_b64_e32 v[78:79], 0
	v_mov_b64_e32 v[80:81], 0
	v_mov_b64_e32 v[82:83], 0
	v_mov_b64_e32 v[84:85], 0
	v_mov_b64_e32 v[86:87], 0
	v_mov_b64_e32 v[88:89], 0
	v_mov_b64_e32 v[90:91], 0
	v_mov_b64_e32 v[92:93], 0
	v_mov_b64_e32 v[94:95], 0
	v_mov_b64_e32 v[96:97], 0
	v_mov_b64_e32 v[98:99], 0
	v_mov_b64_e32 v[100:101], 0
	v_mov_b64_e32 v[102:103], 0
	v_mov_b64_e32 v[104:105], 0
	v_mov_b64_e32 v[106:107], 0
	v_mov_b64_e32 v[108:109], 0
	v_mov_b64_e32 v[110:111], 0
	v_mov_b64_e32 v[112:113], 0
	v_mov_b64_e32 v[114:115], 0
	v_mov_b64_e32 v[116:117], 0
	v_mov_b64_e32 v[118:119], 0
	v_mov_b64_e32 v[120:121], 0
	v_mov_b64_e32 v[122:123], 0
	v_mov_b64_e32 v[124:125], 0
	v_mov_b64_e32 v[126:127], 0
	v_mov_b64_e32 v[128:129], 0
	s_waitcnt vmcnt(0)
	s_barrier
	s_barrier

; #define GAS __attribute__((address_space(1)))
; #define WAIT_V(n) asm volatile("s_waitcnt vmcnt(" #n ")" ::: "memory")
; #define BAR __builtin_amdgcn_s_barrier()
; template <int K, int LD = K>
; __device__ __forceinline__ void gemm_main(const GAS bf16* A, const GAS bf16* Bt, int brow, int bcol, f32x4 (&acc)[2][2][4][2]) {
;     ...
;   const int wid = tid_ >> 6, lane = tid_ & 63, wr = wid >> 2, wc = wid & 3, fr = lane & 15, fq = lane >> 4;
; #pragma unroll
;   for (int a = 0; a < 2; ++a)
; #pragma unroll
;     for (int b = 0; b < 2; ++b)
; #pragma unroll
;       for (int m = 0; m < 4; ++m)
; #pragma unroll
;         for (int n = 0; n < 2; ++n) acc[a][b][m][n] = f32x4{0.f, 0.f, 0.f, 0.f};
;   bf16x8 At[4][2], B0[2][2], B1[2][2];
;   unsigned so0, so1;
;   { int r_, c_; stage_rc(tid_ * 16, r_, c_); so0 = (unsigned)(r_ * LD + c_) * 2u; stage_rc(tid_ * 16 + 8192, r_, c_); so1 = (unsigned)(r_ * LD + c_) * 2u; }
;   const GAS char* pA0 = (const GAS char*)A + (long)brow * LD * 2; const GAS char* pA1 = pA0 + (long)HALF * LD * 2;
;   const GAS char* pB0 = (const GAS char*)Bt + (long)bcol * LD * 2; const GAS char* pB1 = pB0 + (long)HALF * LD * 2;
;   asm volatile("" : "+s"(pA0), "+s"(pA1), "+s"(pB0), "+s"(pB1));
;   constexpr int nt = K / BK;
;   static_assert(K % 128 == 0 && K >= 256, "K");
;   if (wr == 1) BAR;
;   WAIT_V(0); BAR;
;   BAR;
.LBB0_1104:
	s_or_b64 exec, exec, s[22:23]
	v_bfe_i32 v7, v134, 27, 1
	v_lshlrev_b32_e32 v5, 4, v134
	v_lshrrev_b32_e32 v7, 22, v7
	v_add_u32_e32 v7, v5, v7
	v_and_b32_e32 v7, 0xfffffc00, v7
	v_ashrrev_i32_e32 v6, 31, v134
	v_sub_u32_e32 v7, v5, v7
	v_lshrrev_b32_e32 v6, 26, v6
	v_lshrrev_b32_e32 v8, 4, v7
	v_add_u32_e32 v6, v134, v6
	v_bitop3_b32 v8, v8, v7, 32 bitop3:0x6c
	v_ashrrev_i32_e32 v7, 31, v7
	v_ashrrev_i32_e32 v6, 6, v6
	v_lshrrev_b32_e32 v7, 26, v7
	v_lshlrev_b32_e32 v9, 3, v6
	v_add_u32_e32 v7, v8, v7
	v_and_b32_e32 v9, 0x3fffff0, v9
	v_ashrrev_i32_e32 v7, 6, v7
	v_add_u32_e32 v9, v7, v9
	v_mul_i32_i24_e32 v7, 64, v7
	v_sub_u32_e32 v7, v8, v7
	v_lshlrev_b32_e32 v6, 5, v6
	v_ashrrev_i16_sdwa v7, v1, sext(v7) dst_sel:DWORD dst_unused:UNUSED_PAD src0_sel:DWORD src1_sel:BYTE_0
	v_mul_lo_u32 v8, v9, s31
	v_bfe_i32 v7, v7, 0, 16
	v_and_or_b32 v6, v6, 32, v8
	v_add_lshl_u32 v130, v6, v7, 1
	v_add_u32_e32 v6, 0x2000, v5
	v_ashrrev_i32_e32 v7, 31, v6
	v_lshrrev_b32_e32 v7, 22, v7
	v_add_u32_e32 v7, v6, v7
	v_ashrrev_i32_e32 v7, 10, v7
	v_mul_i32_i24_e32 v8, 0x400, v7
	v_sub_u32_e32 v6, v6, v8
	v_lshrrev_b32_e32 v8, 4, v6
	v_bitop3_b32 v6, v8, v6, 32 bitop3:0x6c
	v_ashrrev_i32_e32 v9, 31, v6
	v_lshrrev_b32_e32 v9, 26, v9
	v_lshlrev_b32_e32 v8, 3, v7
	v_add_u32_e32 v9, v6, v9
	v_and_b32_e32 v8, 0x3fffff0, v8
	v_lshrrev_b32_e32 v10, 6, v9
	v_and_b32_e32 v9, 0xc0, v9
	v_add_u32_e32 v8, v10, v8
	v_sub_u32_e32 v6, v6, v9
	v_lshlrev_b32_e32 v7, 5, v7
	v_ashrrev_i16_sdwa v6, v1, sext(v6) dst_sel:DWORD dst_unused:UNUSED_PAD src0_sel:DWORD src1_sel:BYTE_0
	v_mul_lo_u32 v8, v8, s31
	v_bfe_i32 v6, v6, 0, 16
	v_and_or_b32 v7, v7, 32, v8
	v_and_b32_e32 v3, 15, v134
	v_add_lshl_u32 v132, v7, v6, 1
	v_lshlrev_b32_e32 v6, 2, v134
	v_and_b32_e32 v4, 48, v134
	v_lshlrev_b32_e32 v3, 6, v3
	v_and_b32_e32 v6, 32, v6
	v_lshlrev_b32_e32 v11, 6, v134
	v_bitop3_b32 v3, v3, v6, v4 bitop3:0x36
	v_lshlrev_b32_e32 v13, 13, v2
	v_and_or_b32 v2, v11, s38, v4
	v_add_u32_e32 v7, s34, v3
	v_add_u32_e32 v8, s35, v3
	v_add_u32_e32 v9, s36, v3
	v_add_u32_e32 v10, s37, v3
	v_and_b32_e32 v12, 0x3000, v11
	v_add_u32_e32 v3, 0x100, v3
	v_xad_u32 v4, v2, v6, s33
	v_or_b32_e32 v6, 0x800, v13
	v_or_b32_e32 v11, 0x1000, v13
	v_or_b32_e32 v14, 0x1800, v13
	v_mov_b32_e32 v2, 0
	v_add_u32_e32 v145, 0x100, v5
	v_add_u32_e32 v151, s34, v5
	v_add_u32_e32 v153, s35, v5
	v_add_u32_e32 v155, s36, v5
	v_add_u32_e32 v157, s37, v5
	v_mov_b32_e32 v133, v131
	s_mov_b32 s22, -2
	v_add_u32_e32 v144, v7, v12
	v_add_u32_e32 v138, v3, v13
	v_add_u32_e32 v137, v4, v6
	v_add_u32_e32 v136, v4, v11
	v_add_u32_e32 v135, v4, v14
	v_add_u32_e32 v143, 0xc000, v145
	v_add_u32_e32 v142, 0xe000, v145
	v_add_u32_e32 v141, v8, v12
	v_add_u32_e32 v146, 0x2000, v145
	v_add_u32_e32 v140, v9, v12
	v_add_u32_e32 v147, 0x4000, v145
	v_add_u32_e32 v148, 0x6000, v145
	v_add_u32_e32 v139, v10, v12
	v_add_u32_e32 v149, 0x8000, v145
	v_add_u32_e32 v150, 0xa000, v145
	v_add_u32_e32 v152, 0x2000, v151
	v_add_u32_e32 v154, 0x2000, v153
	v_add_u32_e32 v156, 0x2000, v155
	v_add_u32_e32 v158, 0x2000, v157
	v_mov_b32_e32 v3, 0
	v_mov_b64_e32 v[4:5], 0
	v_mov_b64_e32 v[6:7], 0
	v_mov_b64_e32 v[8:9], 0
	v_mov_b64_e32 v[10:11], 0
	v_mov_b64_e32 v[12:13], 0
	v_mov_b64_e32 v[14:15], 0
	v_mov_b64_e32 v[16:17], 0
	v_mov_b64_e32 v[18:19], 0
	v_mov_b64_e32 v[20:21], 0
	v_mov_b64_e32 v[22:23], 0
	v_mov_b64_e32 v[24:25], 0
	v_mov_b64_e32 v[26:27], 0
	v_mov_b64_e32 v[28:29], 0
	v_mov_b64_e32 v[30:31], 0
	v_mov_b64_e32 v[32:33], 0
	v_mov_b64_e32 v[34:35], 0
	v_mov_b64_e32 v[36:37], 0
	v_mov_b64_e32 v[38:39], 0
	v_mov_b64_e32 v[40:41], 0
	v_mov_b64_e32 v[42:43], 0
	v_mov_b64_e32 v[44:45], 0
	v_mov_b64_e32 v[46:47], 0
	v_mov_b64_e32 v[48:49], 0
	v_mov_b64_e32 v[50:51], 0
	v_mov_b64_e32 v[52:53], 0
	v_mov_b64_e32 v[54:55], 0
	v_mov_b64_e32 v[56:57], 0
	v_mov_b64_e32 v[58:59], 0
	v_mov_b64_e32 v[60:61], 0
	v_mov_b64_e32 v[62:63], 0
	v_mov_b64_e32 v[64:65], 0
	v_mov_b64_e32 v[66:67], 0
	v_mov_b64_e32 v[68:69], 0
	v_mov_b64_e32 v[70:71], 0
	v_mov_b64_e32 v[72:73], 0
	v_mov_b64_e32 v[74:75], 0
	v_mov_b64_e32 v[76:77], 0
	v_mov_b64_e32 v[78:79], 0
	v_mov_b64_e32 v[80:81], 0
	v_mov_b64_e32 v[82:83], 0
	v_mov_b64_e32 v[84:85], 0
	v_mov_b64_e32 v[86:87], 0
	v_mov_b64_e32 v[88:89], 0
	v_mov_b64_e32 v[90:91], 0
	v_mov_b64_e32 v[92:93], 0
	v_mov_b64_e32 v[94:95], 0
	v_mov_b64_e32 v[96:97], 0
	v_mov_b64_e32 v[98:99], 0
	v_mov_b64_e32 v[100:101], 0
	v_mov_b64_e32 v[102:103], 0
	v_mov_b64_e32 v[104:105], 0
	v_mov_b64_e32 v[106:107], 0
	v_mov_b64_e32 v[108:109], 0
	v_mov_b64_e32 v[110:111], 0
	v_mov_b64_e32 v[112:113], 0
	v_mov_b64_e32 v[114:115], 0
	v_mov_b64_e32 v[116:117], 0
	v_mov_b64_e32 v[118:119], 0
	v_mov_b64_e32 v[120:121], 0
	v_mov_b64_e32 v[122:123], 0
	v_mov_b64_e32 v[124:125], 0
	v_mov_b64_e32 v[126:127], 0
	v_mov_b64_e32 v[128:129], 0
	s_waitcnt vmcnt(0)
	s_barrier
	s_barrier

; #define GAS __attribute__((address_space(1)))
; #define WAIT_V(n) asm volatile("s_waitcnt vmcnt(" #n ")" ::: "memory")
; #define BAR __builtin_amdgcn_s_barrier()
; template <int K, int LD = K>
; __device__ __forceinline__ void gemm_main(const GAS bf16* A, const GAS bf16* Bt, int brow, int bcol, f32x4 (&acc)[2][2][4][2]) {
;     ...
;   const int wid = tid_ >> 6, lane = tid_ & 63, wr = wid >> 2, wc = wid & 3, fr = lane & 15, fq = lane >> 4;
; #pragma unroll
;   for (int a = 0; a < 2; ++a)
; #pragma unroll
;     for (int b = 0; b < 2; ++b)
; #pragma unroll
;       for (int m = 0; m < 4; ++m)
; #pragma unroll
;         for (int n = 0; n < 2; ++n) acc[a][b][m][n] = f32x4{0.f, 0.f, 0.f, 0.f};
;   bf16x8 At[4][2], B0[2][2], B1[2][2];
;   unsigned so0, so1;
;   { int r_, c_; stage_rc(tid_ * 16, r_, c_); so0 = (unsigned)(r_ * LD + c_) * 2u; stage_rc(tid_ * 16 + 8192, r_, c_); so1 = (unsigned)(r_ * LD + c_) * 2u; }
;   const GAS char* pA0 = (const GAS char*)A + (long)brow * LD * 2; const GAS char* pA1 = pA0 + (long)HALF * LD * 2;
;   const GAS char* pB0 = (const GAS char*)Bt + (long)bcol * LD * 2; const GAS char* pB1 = pB0 + (long)HALF * LD * 2;
;   asm volatile("" : "+s"(pA0), "+s"(pA1), "+s"(pB0), "+s"(pB1));
;   constexpr int nt = K / BK;
;   static_assert(K % 128 == 0 && K >= 256, "K");
;   if (wr == 1) BAR;
;   WAIT_V(0); BAR;
;   BAR;
.LBB0_1225:
	s_or_b64 exec, exec, s[30:31]
	v_bfe_i32 v6, v132, 27, 1
	v_lshlrev_b32_e32 v141, 4, v132
	v_lshrrev_b32_e32 v6, 22, v6
	v_add_u32_e32 v6, v141, v6
	v_and_b32_e32 v6, 0xfffffc00, v6
	v_sub_u32_e32 v6, v141, v6
	v_lshrrev_b32_e32 v7, 4, v6
	v_bitop3_b32 v7, v7, v6, 32 bitop3:0x6c
	v_ashrrev_i32_e32 v6, 31, v6
	v_ashrrev_i32_e32 v5, 31, v132
	v_lshrrev_b32_e32 v6, 26, v6
	v_lshrrev_b32_e32 v5, 26, v5
	v_add_u32_e32 v6, v7, v6
	v_add_u32_e32 v5, v132, v5
	v_ashrrev_i32_e32 v6, 6, v6
	v_ashrrev_i32_e32 v5, 6, v5
	v_mul_i32_i24_e32 v9, 64, v6
	v_lshlrev_b32_e32 v8, 3, v5
	v_lshlrev_b32_e32 v5, 5, v5
	v_sub_u32_e32 v7, v7, v9
	v_and_b32_e32 v8, 0x1ffff0, v8
	v_and_b32_e32 v5, 32, v5
	v_ashrrev_i16_sdwa v7, v1, sext(v7) dst_sel:DWORD dst_unused:UNUSED_PAD src0_sel:DWORD src1_sel:BYTE_0
	v_add_u32_sdwa v5, v5, sext(v7) dst_sel:DWORD dst_unused:UNUSED_PAD src0_sel:DWORD src1_sel:WORD_0
	v_add_lshl_u32 v6, v6, v8, 11
	v_lshl_add_u32 v138, v5, 1, v6
	v_add_u32_e32 v5, 0x2000, v141
	v_ashrrev_i32_e32 v6, 31, v5
	v_lshrrev_b32_e32 v6, 22, v6
	v_add_u32_e32 v6, v5, v6
	v_ashrrev_i32_e32 v6, 10, v6
	v_mul_i32_i24_e32 v7, 0x400, v6
	v_sub_u32_e32 v5, v5, v7
	v_lshrrev_b32_e32 v7, 4, v5
	v_bitop3_b32 v5, v7, v5, 32 bitop3:0x6c
	v_ashrrev_i32_e32 v8, 31, v5
	v_lshrrev_b32_e32 v8, 26, v8
	v_add_u32_e32 v8, v5, v8
	v_lshrrev_b32_e32 v9, 6, v8
	v_and_b32_e32 v8, 0xc0, v8
	v_lshlrev_b32_e32 v7, 3, v6
	v_lshlrev_b32_e32 v6, 5, v6
	v_sub_u32_e32 v5, v5, v8
	v_and_b32_e32 v7, 0x1ffff0, v7
	v_and_b32_e32 v6, 32, v6
	v_ashrrev_i16_sdwa v5, v1, sext(v5) dst_sel:DWORD dst_unused:UNUSED_PAD src0_sel:DWORD src1_sel:BYTE_0
	v_add_u32_sdwa v5, v6, sext(v5) dst_sel:DWORD dst_unused:UNUSED_PAD src0_sel:DWORD src1_sel:WORD_0
	v_add_lshl_u32 v6, v9, v7, 11
	v_and_b32_e32 v3, 15, v132
	v_lshl_add_u32 v130, v5, 1, v6
	v_lshlrev_b32_e32 v5, 2, v132
	v_and_b32_e32 v4, 48, v132
	v_lshlrev_b32_e32 v3, 6, v3
	v_and_b32_e32 v5, 32, v5
	v_lshlrev_b32_e32 v10, 6, v132
	v_bitop3_b32 v3, v3, v5, v4 bitop3:0x36
	v_lshlrev_b32_e32 v12, 13, v2
	v_and_or_b32 v2, v10, s46, v4
	v_add_u32_e32 v6, s38, v3
	v_add_u32_e32 v7, s39, v3
	v_add_u32_e32 v8, s40, v3
	v_add_u32_e32 v9, s41, v3
	v_and_b32_e32 v11, 0x3000, v10
	v_add_u32_e32 v3, 0x100, v3
	v_xad_u32 v4, v2, v5, s42
	v_or_b32_e32 v5, 0x800, v12
	v_or_b32_e32 v10, 0x1000, v12
	v_or_b32_e32 v13, 0x1800, v12
	v_mov_b32_e32 v2, 0
	v_mov_b32_e32 v131, v139
	s_mov_b32 s21, -2
	v_add_u32_e32 v143, v6, v11
	v_add_u32_e32 v136, v3, v12
	v_add_u32_e32 v135, v4, v5
	v_add_u32_e32 v134, v4, v10
	v_add_u32_e32 v133, v4, v13
	v_add_u32_e32 v142, v7, v11
	v_add_u32_e32 v140, v8, v11
	v_add_u32_e32 v137, v9, v11
	v_mov_b32_e32 v3, 0
	v_mov_b64_e32 v[4:5], 0
	v_mov_b64_e32 v[6:7], 0
	v_mov_b64_e32 v[8:9], 0
	v_mov_b64_e32 v[10:11], 0
	v_mov_b64_e32 v[12:13], 0
	v_mov_b64_e32 v[14:15], 0
	v_mov_b64_e32 v[16:17], 0
	v_mov_b64_e32 v[18:19], 0
	v_mov_b64_e32 v[20:21], 0
	v_mov_b64_e32 v[22:23], 0
	v_mov_b64_e32 v[24:25], 0
	v_mov_b64_e32 v[26:27], 0
	v_mov_b64_e32 v[28:29], 0
	v_mov_b64_e32 v[30:31], 0
	v_mov_b64_e32 v[32:33], 0
	v_mov_b64_e32 v[34:35], 0
	v_mov_b64_e32 v[36:37], 0
	v_mov_b64_e32 v[38:39], 0
	v_mov_b64_e32 v[40:41], 0
	v_mov_b64_e32 v[42:43], 0
	v_mov_b64_e32 v[44:45], 0
	v_mov_b64_e32 v[46:47], 0
	v_mov_b64_e32 v[48:49], 0
	v_mov_b64_e32 v[50:51], 0
	v_mov_b64_e32 v[52:53], 0
	v_mov_b64_e32 v[54:55], 0
	v_mov_b64_e32 v[56:57], 0
	v_mov_b64_e32 v[58:59], 0
	v_mov_b64_e32 v[60:61], 0
	v_mov_b64_e32 v[62:63], 0
	v_mov_b64_e32 v[64:65], 0
	v_mov_b64_e32 v[66:67], 0
	v_mov_b64_e32 v[68:69], 0
	v_mov_b64_e32 v[70:71], 0
	v_mov_b64_e32 v[72:73], 0
	v_mov_b64_e32 v[74:75], 0
	v_mov_b64_e32 v[76:77], 0
	v_mov_b64_e32 v[78:79], 0
	v_mov_b64_e32 v[80:81], 0
	v_mov_b64_e32 v[82:83], 0
	v_mov_b64_e32 v[84:85], 0
	v_mov_b64_e32 v[86:87], 0
	v_mov_b64_e32 v[88:89], 0
	v_mov_b64_e32 v[90:91], 0
	v_mov_b64_e32 v[92:93], 0
	v_mov_b64_e32 v[94:95], 0
	v_mov_b64_e32 v[96:97], 0
	v_mov_b64_e32 v[98:99], 0
	v_mov_b64_e32 v[100:101], 0
	v_mov_b64_e32 v[102:103], 0
	v_mov_b64_e32 v[104:105], 0
	v_mov_b64_e32 v[106:107], 0
	v_mov_b64_e32 v[108:109], 0
	v_mov_b64_e32 v[110:111], 0
	v_mov_b64_e32 v[112:113], 0
	v_mov_b64_e32 v[114:115], 0
	v_mov_b64_e32 v[116:117], 0
	v_mov_b64_e32 v[118:119], 0
	v_mov_b64_e32 v[120:121], 0
	v_mov_b64_e32 v[122:123], 0
	v_mov_b64_e32 v[124:125], 0
	v_mov_b64_e32 v[126:127], 0
	v_mov_b64_e32 v[128:129], 0
	s_waitcnt vmcnt(0)
	s_barrier
	s_barrier
